# baseline + attention half-step stagger only
# baseline (speedup 1.0000x reference)
; #define AT_STAGE(gbase, so, i, ldsoff) do { const int _ii = (i) < NT ? (i) : NT - 1; const size_t _go = (size_t)((tstart + _ii) & tmask) * (64 * 1024); _Pragma("unroll") for (int _i = 0; _i < 2; ++_i) \
;         __builtin_amdgcn_global_load_lds((const unsigned*)((gbase) + _go + (so)[_i]), (LAS unsigned*)(lds + (ldsoff) + (2 * w + _i) * 1024), 16, 0, 0); } while (0)
; #define AT_BAR(N) asm volatile("s_waitcnt vmcnt(" #N ") lgkmcnt(0)\n\ts_barrier" ::: "memory")
; __device__ __forceinline__ void attn_unit(LAS unsigned char* lds, int seq, int h, int qb, bf16_t* UQ, const bf16_t* KB, const bf16_t* VB, const float* rel_bias, const float* subln, float lam, float bmax) {
;     ...
;     for (int i = 1; i < NT - 1; ++i) {
;         AT_STAGE(kg, kso, i + 3, k_i); AT_STAGE(vg, vso, i + 2, AT_V0 + ((i + 2) & 3) * AT_TILE);
;         AT_TB((tstart + i + 1) & tmask);
;         attn_step<true, true>(lds + k_n, lds0 + AT_V0 + ((i - 1) & 3) * AT_TILE, kfo, vo, qf, s, pf, o, ol, tbv);
;         AT_BAR(4);
;         { const int tmp = k_i; k_i = k_n; k_n = k_p; k_p = tmp; }
;     }
;     attn_step<false, true>(lds, lds0 + AT_V0 + ((NT - 2) & 3) * AT_TILE, kfo, vo, qf, s, pf, o, ol, tbv);
;     attn_pv(lds0 + AT_V0 + ((NT - 1) & 3) * AT_TILE, vo, pf, o, ol);
.LBB0_502:
	s_cmp_gt_u32 s98, 3
	s_cbranch_scc1 .Lat_yskip_s
	s_barrier

; #define LAS __attribute__((address_space(3)))
; __device__ __forceinline__ unsigned cvtpk(float lo, float hi) { f32x2 v = {lo, hi}; bf16x2_t b = __builtin_convertvector(v, bf16x2_t); return __builtin_bit_cast(unsigned, b); }
; __device__ __forceinline__ float fast_exp2(float x) { return __builtin_amdgcn_exp2f(x); }
; #define AT_STAGE(gbase, so, i, ldsoff) do { const int _ii = (i) < NT ? (i) : NT - 1; const size_t _go = (size_t)((tstart + _ii) & tmask) * (64 * 1024); _Pragma("unroll") for (int _i = 0; _i < 2; ++_i) \
;         __builtin_amdgcn_global_load_lds((const unsigned*)((gbase) + _go + (so)[_i]), (LAS unsigned*)(lds + (ldsoff) + (2 * w + _i) * 1024), 16, 0, 0); } while (0)
; template <bool QK, bool PV> ...
;     ...
;         {
;             const int c = dt >> 2, kt = dt & 3;
; #pragma unroll
;             for (int j = 0; j < 4; ++j) s[c][kt][j] = fast_exp2(s[c][kt][j]);
;             if (kt & 1) { const int si = kt >> 1;
;                 u32x4 wv; wv.x = cvtpk(s[c][2 * si][0], s[c][2 * si][1]); wv.y = cvtpk(s[c][2 * si][2], s[c][2 * si][3]);
;                 wv.z = cvtpk(s[c][2 * si + 1][0], s[c][2 * si + 1][1]); wv.w = cvtpk(s[c][2 * si + 1][2], s[c][2 * si + 1][3]);
;                 pn[c][si] = __builtin_bit_cast(bf16x8, wv); }
;         }
;     }
;     ...
; #pragma unroll
;     for (int c = 0; c < 2; ++c)
; #pragma unroll
;         for (int si = 0; si < 2; ++si) pf[c][si] = pn[c][si];
;     if constexpr (QK) {
; #pragma unroll
;         for (int kt = 0; kt < 4; ++kt)
; #pragma unroll
;             for (int c = 0; c < 2; ++c) {
;                 f32x4 a = tbv[kt];
; #pragma unroll
;                 for (int kk = 0; kk < 2; ++kk) { const bf16x8 kf = *(const LAS bf16x8*)(kbuf + kfo[c][kk] + kt * 4096); a = __builtin_amdgcn_mfma_f32_16x16x32_bf16(kf, qf[c][kk], a, 0, 0, 0); }
;                 s[c][kt] = a;
;             }
;     }
; __device__ __forceinline__ void attn_unit(LAS unsigned char* lds, int seq, int h, int qb, bf16_t* UQ, const bf16_t* KB, const bf16_t* VB, const float* rel_bias, const float* subln, float lam, float bmax) {
;     ...
;     AT_BAR(0);
;     AT_STAGE(kg, kso, 3, AT_K0); AT_STAGE(vg, vso, 2, AT_V0 + 2 * AT_TILE);
;     AT_TB((tstart + 1) & tmask);
;     attn_step<true, false>(lds + AT_K0 + AT_TILE, 0u, kfo, vo, qf, s, pf, o, ol, tbv);
;     AT_BAR(4);
;     int k_i = AT_K0 + AT_TILE, k_n = AT_K0 + 2 * AT_TILE, k_p = AT_K0;
.LBB0_513:
	v_exp_f32_e32 v82, v42
	v_exp_f32_e32 v83, v43
	v_exp_f32_e32 v84, v44
	v_exp_f32_e32 v85, v45
	ds_read_b128 v[42:45], v67 offset:16384
	v_exp_f32_e32 v94, v22
	v_exp_f32_e32 v95, v23
	v_exp_f32_e32 v96, v24
	v_exp_f32_e32 v97, v25
	ds_read_b128 v[22:25], v69 offset:16384
	v_exp_f32_e32 v98, v46
	v_exp_f32_e32 v99, v47
	v_exp_f32_e32 v100, v48
	v_exp_f32_e32 v101, v49
	ds_read_b128 v[46:49], v66 offset:16384
	ds_read_b128 v[70:73], v67 offset:20480
	s_waitcnt lgkmcnt(0)
	v_mfma_f32_16x16x32_bf16 v[42:45], v[42:45], v[2:5], v[58:61]
	v_exp_f32_e32 v102, v38
	v_exp_f32_e32 v103, v39
	v_exp_f32_e32 v104, v40
	v_exp_f32_e32 v105, v41
	ds_read_b128 v[38:41], v68 offset:16384
	ds_read_b128 v[78:81], v69 offset:20480
	v_mfma_f32_16x16x32_bf16 v[74:77], v[22:25], v[6:9], v[42:45]
	v_exp_f32_e32 v106, v18
	v_exp_f32_e32 v107, v19
	v_exp_f32_e32 v108, v28
	ds_read_b128 v[42:45], v66 offset:20480
	v_mfma_f32_16x16x32_bf16 v[22:25], v[46:49], v[10:13], v[58:61]
	v_exp_f32_e32 v109, v29
	s_and_b32 s2, s43, 31
	s_lshl_b32 s52, s2, 1
	v_exp_f32_e32 v58, v20
	v_exp_f32_e32 v59, v21
	ds_read_b128 v[18:21], v68 offset:20480
	s_waitcnt lgkmcnt(0)
	v_mfma_f32_16x16x32_bf16 v[22:25], v[38:41], v[14:17], v[22:25]
	v_exp_f32_e32 v60, v26
	v_exp_f32_e32 v61, v27
	s_add_i32 s52, s52, 2
	v_mfma_f32_16x16x32_bf16 v[38:41], v[70:73], v[2:5], v[50:53]
	v_exp_f32_e32 v70, v30
	v_exp_f32_e32 v71, v31
	v_exp_f32_e32 v72, v32
	v_exp_f32_e32 v73, v33
	ds_read_b128 v[30:33], v67 offset:24576
	v_mfma_f32_16x16x32_bf16 v[86:89], v[78:81], v[6:9], v[38:41]
	v_exp_f32_e32 v78, v34
	v_exp_f32_e32 v79, v35
	v_exp_f32_e32 v80, v36
	ds_read_b128 v[38:41], v69 offset:24576
	v_mfma_f32_16x16x32_bf16 v[26:29], v[42:45], v[10:13], v[50:53]
	ds_read_b128 v[42:45], v66 offset:24576
	ds_read_b128 v[46:49], v67 offset:28672
	v_exp_f32_e32 v67, v37
	s_addk_i32 s53, 0xff42
	v_mfma_f32_16x16x32_bf16 v[26:29], v[18:21], v[14:17], v[26:29]
	s_add_i32 s54, s45, -1
	s_movk_i32 s59, 0x4000
	s_mov_b32 s58, 0x8000
	s_waitcnt lgkmcnt(0)
	v_mfma_f32_16x16x32_bf16 v[18:21], v[30:33], v[2:5], v[62:65]
	ds_read_b128 v[30:33], v68 offset:24576
	ds_read_b128 v[50:53], v69 offset:28672
	s_mov_b32 s55, 0x10000
	s_mov_b32 s60, 0
	v_mfma_f32_16x16x32_bf16 v[90:93], v[38:41], v[6:9], v[18:21]
	s_mov_b32 s2, 0
	s_nop 1
	v_cvt_pk_bf16_f32 v18, v70, v71
	v_cvt_pk_bf16_f32 v19, v72, v73
	ds_read_b128 v[70:73], v66 offset:28672
	v_mfma_f32_16x16x32_bf16 v[34:37], v[42:45], v[10:13], v[62:65]
	v_cvt_pk_bf16_f32 v20, v78, v79
	v_cvt_pk_bf16_f32 v21, v80, v67
	v_cvt_pk_bf16_f32 v42, v106, v107
	ds_read_b128 v[62:65], v68 offset:28672
	s_waitcnt lgkmcnt(0)
	v_mfma_f32_16x16x32_bf16 v[38:41], v[30:33], v[14:17], v[34:37]
	s_waitcnt vmcnt(4) lgkmcnt(0)
	s_barrier
	v_cvt_pk_bf16_f32 v43, v58, v59
	v_cvt_pk_bf16_f32 v44, v60, v61
	v_mfma_f32_16x16x32_bf16 v[30:33], v[46:49], v[2:5], v[54:57]
	v_cvt_pk_bf16_f32 v34, v94, v95
	v_cvt_pk_bf16_f32 v35, v96, v97
	v_cvt_pk_bf16_f32 v45, v108, v109
	v_mfma_f32_16x16x32_bf16 v[94:97], v[50:53], v[6:9], v[30:33]
	v_cvt_pk_bf16_f32 v36, v102, v103
	v_cvt_pk_bf16_f32 v37, v104, v105
	v_cvt_pk_bf16_f32 v58, v82, v83
	v_mfma_f32_16x16x32_bf16 v[30:33], v[70:73], v[10:13], v[54:57]
	v_cvt_pk_bf16_f32 v59, v84, v85
	v_cvt_pk_bf16_f32 v60, v98, v99
	v_cvt_pk_bf16_f32 v61, v100, v101
	v_mfma_f32_16x16x32_bf16 v[62:65], v[62:65], v[14:17], v[30:33]
	s_nop 3
	v_mov_b32_e32 v30, 0
	v_mov_b32_e32 v31, v30
	v_mov_b32_e32 v32, v30
	v_mov_b32_e32 v33, v30
	v_mov_b32_e32 v46, v30
	v_mov_b32_e32 v47, v30
	v_mov_b32_e32 v48, v30
	v_mov_b32_e32 v49, v30
	v_mov_b32_e32 v54, v30
	v_mov_b32_e32 v55, v30
	v_mov_b32_e32 v56, v30
	v_mov_b32_e32 v57, v30
	v_mov_b32_e32 v50, v30
	v_mov_b32_e32 v51, v30
	v_mov_b32_e32 v52, v30
	v_mov_b32_e32 v53, v30
	v_mov_b32_e32 v66, v30
	v_mov_b32_e32 v67, v30
	v_mov_b32_e32 v68, v30
	v_mov_b32_e32 v69, v30
	v_mov_b32_e32 v70, v30
	v_mov_b32_e32 v71, v30
	v_mov_b32_e32 v72, v30
	v_mov_b32_e32 v73, v30
	v_mov_b32_e32 v78, v30
	v_mov_b32_e32 v79, v30
	v_mov_b32_e32 v80, v30
	v_mov_b32_e32 v81, v30
	v_mov_b32_e32 v82, v30
	v_mov_b32_e32 v83, v30
	v_mov_b32_e32 v84, v30
	v_mov_b32_e32 v85, v30
	v_mov_b32_e32 v98, v30
	v_mov_b32_e32 v99, v30
	v_mov_b32_e32 v100, v30
	v_mov_b32_e32 v101, v30
	v_mov_b32_e32 v102, v30
	v_mov_b32_e32 v103, v30
	v_mov_b32_e32 v104, v30
	v_mov_b32_e32 v105, v30
	v_mov_b32_e32 v106, v30
	v_mov_b32_e32 v107, v30
	v_mov_b32_e32 v108, v30
	v_mov_b32_e32 v109, v30
	v_mov_b32_e32 v110, v30
	v_mov_b32_e32 v111, v30
	v_mov_b32_e32 v112, v30
	v_mov_b32_e32 v113, v30
	v_mov_b32_e32 v114, v30
	v_mov_b32_e32 v115, v30
	v_mov_b32_e32 v116, v30
	v_mov_b32_e32 v117, v30
	v_mov_b32_e32 v118, v30
	v_mov_b32_e32 v119, v30
	v_mov_b32_e32 v120, v30
	v_mov_b32_e32 v121, v30
	v_mov_b32_e32 v122, v30
	v_mov_b32_e32 v123, v30
	v_mov_b32_e32 v124, v30
	v_mov_b32_e32 v125, v30
	v_mov_b32_e32 v134, v30
	v_mov_b32_e32 v135, v30
	v_mov_b32_e32 v136, v30
	v_mov_b32_e32 v137, v30
	v_mov_b32_e32 v130, v30
	v_mov_b32_e32 v131, v30
	v_mov_b32_e32 v132, v30
	v_mov_b32_e32 v133, v30
	v_mov_b32_e32 v126, v30
	v_mov_b32_e32 v127, v30
	v_mov_b32_e32 v128, v30
	v_mov_b32_e32 v129, v30
	v_readfirstlane_b32 s98, v171
	s_nop 3
	s_lshr_b32 s98, s98, 6
	s_cmp_lt_u32 s98, 4
	s_cbranch_scc1 .Lat_xskip_s
	s_barrier
; #define AT_STAGE(gbase, so, i, ldsoff) do { const int _ii = (i) < NT ? (i) : NT - 1; const size_t _go = (size_t)((tstart + _ii) & tmask) * (64 * 1024); _Pragma("unroll") for (int _i = 0; _i < 2; ++_i) \
;         __builtin_amdgcn_global_load_lds((const unsigned*)((gbase) + _go + (so)[_i]), (LAS unsigned*)(lds + (ldsoff) + (2 * w + _i) * 1024), 16, 0, 0); } while (0)
; __device__ __forceinline__ void attn_unit(LAS unsigned char* lds, int seq, int h, int qb, bf16_t* UQ, const bf16_t* KB, const bf16_t* VB, const float* rel_bias, const float* subln, float lam, float bmax) {
;     ...
;     for (int i = 1; i < NT - 1; ++i) {
;         AT_STAGE(kg, kso, i + 3, k_i); AT_STAGE(vg, vso, i + 2, AT_V0 + ((i + 2) & 3) * AT_TILE);
;         AT_TB((tstart + i + 1) & tmask);
.Lat_xskip_s:
.LBB0_514:
	s_mov_b32 s61, s58
	s_add_i32 s3, s60, 3
	s_min_u32 s3, s3, s45
	s_add_i32 s3, s3, s46
	s_and_b32 s3, s3, s45
	s_lshl_b32 s3, s3, 16
	s_add_u32 s22, s20, s3
	s_addc_u32 s23, s50, 0
	s_add_i32 s3, s55, 0xffffc000
	s_and_b32 s3, s3, 0xc000
	s_add_i32 s3, s49, s3
	s_add_i32 m0, s3, 0xc000
	s_nop 0
	global_load_lds_dwordx4 v164, s[22:23]
	s_add_i32 m0, s3, 0xc400
	s_mov_b32 s58, s2
	global_load_lds_dwordx4 v168, s[22:23]
	s_add_i32 s2, s52, s60
	s_and_b32 s62, s2, s45
	s_lshl_b32 s2, s62, 6
	s_sub_i32 s3, s2, s51
	s_cmp_lt_i32 s2, s53
	s_cselect_b64 s[22:23], -1, 0
	s_cmpk_gt_i32 s3, 0x7f
	s_cselect_b64 s[2:3], -1, 0
	s_or_b64 s[64:65], s[22:23], s[2:3]
	s_mov_b64 s[22:23], -1
	s_and_b64 vcc, exec, s[64:65]
	s_cbranch_vccnz .LBB0_516
	v_lshl_add_u32 v142, s62, 8, v161
	v_add_u32_e32 v139, 4, v142
	v_add_u32_e32 v140, 8, v142
	v_add_u32_e32 v141, 12, v142
	v_add_u32_e32 v146, 0x4c, v142
	v_med3_i32 v138, v142, 0, v213
	v_med3_i32 v139, v139, 0, v213
	v_med3_i32 v140, v140, 0, v213
	v_med3_i32 v141, v141, 0, v213
	v_add_u32_e32 v143, 64, v142
	v_add_u32_e32 v144, 0x44, v142
	v_add_u32_e32 v145, 0x48, v142
	v_med3_i32 v146, v146, 0, v213
	v_add_u32_e32 v138, s27, v138
	v_add_u32_e32 v139, s27, v139
	v_add_u32_e32 v140, s27, v140
	v_add_u32_e32 v141, s27, v141
	v_med3_i32 v143, v143, 0, v213
	v_med3_i32 v144, v144, 0, v213
	v_med3_i32 v145, v145, 0, v213
	v_add_u32_e32 v150, s27, v146
	v_add_u32_e32 v143, s27, v143
	v_add_u32_e32 v144, s27, v144
	v_add_u32_e32 v145, s27, v145
	ds_read_b32 v146, v138
	ds_read_b32 v147, v139
	ds_read_b32 v148, v140
	ds_read_b32 v149, v141
	ds_read_b32 v138, v143
	ds_read_b32 v139, v144
	ds_read_b32 v140, v145
	ds_read_b32 v141, v150
	v_add_u32_e32 v150, 0x8c, v142
	v_med3_i32 v150, v150, 0, v213
	v_add_u32_e32 v153, s27, v150
	v_add_u32_e32 v150, 0xc0, v142
	v_med3_i32 v150, v150, 0, v213
	v_add_u32_e32 v216, s27, v150
	v_add_u32_e32 v150, 0xc4, v142
	v_add_u32_e32 v143, 0x80, v142
	v_add_u32_e32 v144, 0x84, v142
	v_add_u32_e32 v145, 0x88, v142
	v_med3_i32 v150, v150, 0, v213
	v_med3_i32 v143, v143, 0, v213
	v_med3_i32 v144, v144, 0, v213
	v_med3_i32 v145, v145, 0, v213
	v_add_u32_e32 v217, s27, v150
	v_add_u32_e32 v150, 0xc8, v142
	v_add_u32_e32 v142, 0xcc, v142
	v_add_u32_e32 v143, s27, v143
	v_add_u32_e32 v144, s27, v144
	v_add_u32_e32 v145, s27, v145
	v_med3_i32 v150, v150, 0, v213
	v_med3_i32 v142, v142, 0, v213
	v_add_u32_e32 v218, s27, v150
	v_add_u32_e32 v219, s27, v142
	ds_read_b32 v150, v143
	ds_read_b32 v151, v144
	ds_read_b32 v152, v145
	ds_read_b32 v153, v153
	ds_read_b32 v142, v216
	ds_read_b32 v143, v217
	ds_read_b32 v144, v218
	ds_read_b32 v145, v219
	s_mov_b64 s[22:23], 0

; #define AT_TR4(slot, d) do { const unsigned _a = vaddr + (unsigned)vo[d]; AT_TR(r[slot][0], _a, 0); AT_TR(r[slot][1], _a, 16 * 256); AT_TR(r[slot][2], _a, 32 * 256); AT_TR(r[slot][3], _a, 48 * 256); } while (0)
; #define AT_TR4(slot, d) do { const unsigned _a = vaddr + (unsigned)vo[d]; AT_TR(r[slot][0], _a, 0); AT_TR(r[slot][1], _a, 16 * 256); AT_TR(r[slot][2], _a, 32 * 256); AT_TR(r[slot][3], _a, 48 * 256); } while (0)
; template <bool QK, bool PV> ...
;     ...
;     if constexpr (PV) { AT_TR4(0, 0); AT_TR4(1, 1);
;         const bf16x8 ones = (bf16x8){0x3f80, 0x3f80, 0x3f80, 0x3f80, 0x3f80, 0x3f80, 0x3f80, 0x3f80};
; #pragma unroll
;         for (int c = 0; c < 2; ++c)
; #pragma unroll
;             for (int si = 0; si < 2; ++si) ol[c] = __builtin_amdgcn_mfma_f32_16x16x32_bf16(ones, pf[c][si], ol[c], 0, 0, 0); }
; #pragma unroll
;     for (int dt = 0; dt < 8; ++dt) {
;         if constexpr (PV) {
;             const int cb = dt % 3;
;             if (dt < 6) { AT_TR4((dt + 2) % 3, dt + 2); asm volatile("s_waitcnt lgkmcnt(8)" : "+v"(r[cb][0]), "+v"(r[cb][1]), "+v"(r[cb][2]), "+v"(r[cb][3])); }
;             else if (dt == 6) asm volatile("s_waitcnt lgkmcnt(4)" : "+v"(r[cb][0]), "+v"(r[cb][1]), "+v"(r[cb][2]), "+v"(r[cb][3]));
;             else asm volatile("s_waitcnt lgkmcnt(0)" : "+v"(r[cb][0]), "+v"(r[cb][1]), "+v"(r[cb][2]), "+v"(r[cb][3]));
; #pragma unroll
;             for (int si = 0; si < 2; ++si) {
;                 const s16x4 lo = r[cb][2 * si], hi = r[cb][2 * si + 1];
;                 const bf16x8 vf = (bf16x8){lo[0], lo[1], lo[2], lo[3], hi[0], hi[1], hi[2], hi[3]};
;                 o[0][dt] = __builtin_amdgcn_mfma_f32_16x16x32_bf16(vf, pf[0][si], o[0][dt], 0, 0, 0);
;                 o[1][dt] = __builtin_amdgcn_mfma_f32_16x16x32_bf16(vf, pf[1][si], o[1][dt], 0, 0, 0);
;             }
;         }
.LBB0_518:
	v_mov_b64_e32 v[218:219], s[6:7]
	v_mov_b64_e32 v[216:217], s[4:5]
	s_and_b32 s2, s55, 0xc000
	s_add_i32 s2, s2, 0
	s_add_i32 s2, s2, 0xc000
	v_add_u32_e32 v228, s2, v186
	v_mfma_f32_16x16x32_bf16 v[134:137], v[216:219], v[58:61], v[134:137]
	ds_read_b64_tr_b16 v[220:221], v228 offset:0
	ds_read_b64_tr_b16 v[222:223], v228 offset:0x1000
	ds_read_b64_tr_b16 v[224:225], v228 offset:0x2000
	v_mfma_f32_16x16x32_bf16 v[130:133], v[216:219], v[42:45], v[130:133]
	ds_read_b64_tr_b16 v[226:227], v228 offset:0x3000
	v_add_u32_e32 v236, s2, v187
	ds_read_b64_tr_b16 v[228:229], v236 offset:0
	v_mfma_f32_16x16x32_bf16 v[134:137], v[216:219], v[34:37], v[134:137]
	ds_read_b64_tr_b16 v[230:231], v236 offset:0x1000
	ds_read_b64_tr_b16 v[232:233], v236 offset:0x2000
	ds_read_b64_tr_b16 v[234:235], v236 offset:0x3000
	v_mfma_f32_16x16x32_bf16 v[130:133], v[216:219], v[18:21], v[130:133]
	v_add_u32_e32 v240, s2, v188
	ds_read_b64_tr_b16 v[216:217], v240 offset:0
	ds_read_b64_tr_b16 v[218:219], v240 offset:0x1000
	ds_read_b64_tr_b16 v[236:237], v240 offset:0x2000
	ds_read_b64_tr_b16 v[238:239], v240 offset:0x3000
	s_waitcnt lgkmcnt(8)
	v_add_u32_e32 v240, s2, v189
	v_mfma_f32_16x16x32_bf16 v[126:129], v[220:223], v[58:61], v[126:129]
	v_exp_f32_e32 v241, v28
	v_exp_f32_e32 v242, v29
	s_addk_i32 s55, 0x4000
	v_mfma_f32_16x16x32_bf16 v[122:125], v[220:223], v[42:45], v[122:125]
	ds_read_b64_tr_b16 v[220:221], v240 offset:0
	ds_read_b64_tr_b16 v[222:223], v240 offset:0x1000
	s_add_i32 s60, s60, 1
	v_mfma_f32_16x16x32_bf16 v[126:129], v[224:227], v[34:37], v[126:129]
	v_mfma_f32_16x16x32_bf16 v[122:125], v[224:227], v[18:21], v[122:125]
	ds_read_b64_tr_b16 v[224:225], v240 offset:0x2000
	ds_read_b64_tr_b16 v[226:227], v240 offset:0x3000
	s_waitcnt lgkmcnt(8)
	v_add_u32_e32 v240, s2, v190
	v_mfma_f32_16x16x32_bf16 v[114:117], v[228:231], v[58:61], v[114:117]
	v_mfma_f32_16x16x32_bf16 v[118:121], v[228:231], v[42:45], v[118:121]
	ds_read_b64_tr_b16 v[228:229], v240 offset:0
	ds_read_b64_tr_b16 v[230:231], v240 offset:0x1000
	v_mfma_f32_16x16x32_bf16 v[114:117], v[232:235], v[34:37], v[114:117]
	v_mfma_f32_16x16x32_bf16 v[118:121], v[232:235], v[18:21], v[118:121]
	ds_read_b64_tr_b16 v[232:233], v240 offset:0x2000
	ds_read_b64_tr_b16 v[234:235], v240 offset:0x3000
	s_waitcnt lgkmcnt(8)
	v_add_u32_e32 v240, s2, v191
	v_mfma_f32_16x16x32_bf16 v[106:109], v[216:219], v[58:61], v[106:109]
	v_mfma_f32_16x16x32_bf16 v[110:113], v[216:219], v[42:45], v[110:113]
	ds_read_b64_tr_b16 v[216:217], v240 offset:0
	ds_read_b64_tr_b16 v[218:219], v240 offset:0x1000
	v_mfma_f32_16x16x32_bf16 v[106:109], v[236:239], v[34:37], v[106:109]
	v_mfma_f32_16x16x32_bf16 v[110:113], v[236:239], v[18:21], v[110:113]
	ds_read_b64_tr_b16 v[236:237], v240 offset:0x2000
	ds_read_b64_tr_b16 v[238:239], v240 offset:0x3000
	s_waitcnt lgkmcnt(8)
	v_add_u32_e32 v240, s2, v192
	v_mfma_f32_16x16x32_bf16 v[98:101], v[220:223], v[58:61], v[98:101]
	v_mfma_f32_16x16x32_bf16 v[102:105], v[220:223], v[42:45], v[102:105]
	ds_read_b64_tr_b16 v[220:221], v240 offset:0
	ds_read_b64_tr_b16 v[222:223], v240 offset:0x1000
	v_mfma_f32_16x16x32_bf16 v[98:101], v[224:227], v[34:37], v[98:101]
	v_mfma_f32_16x16x32_bf16 v[102:105], v[224:227], v[18:21], v[102:105]
	ds_read_b64_tr_b16 v[224:225], v240 offset:0x2000
	ds_read_b64_tr_b16 v[226:227], v240 offset:0x3000
	s_waitcnt lgkmcnt(8)
	v_add_u32_e32 v240, s2, v193
	v_mfma_f32_16x16x32_bf16 v[78:81], v[228:231], v[58:61], v[78:81]
	s_add_i32 s2, s61, 0
	s_cmp_lg_u32 s54, s60
	v_mfma_f32_16x16x32_bf16 v[82:85], v[228:231], v[42:45], v[82:85]
	ds_read_b64_tr_b16 v[228:229], v240 offset:0
	ds_read_b64_tr_b16 v[230:231], v240 offset:0x1000
	v_mfma_f32_16x16x32_bf16 v[78:81], v[232:235], v[34:37], v[78:81]
	v_mfma_f32_16x16x32_bf16 v[82:85], v[232:235], v[18:21], v[82:85]
	ds_read_b64_tr_b16 v[232:233], v240 offset:0x2000
	ds_read_b64_tr_b16 v[234:235], v240 offset:0x3000
	s_waitcnt lgkmcnt(8)
	s_waitcnt lgkmcnt(4)
	v_exp_f32_e32 v240, v22
	v_mfma_f32_16x16x32_bf16 v[54:57], v[220:223], v[58:61], v[54:57]
	s_waitcnt lgkmcnt(0)
	s_barrier
; #define LAS __attribute__((address_space(3)))
; __device__ __forceinline__ unsigned cvtpk(float lo, float hi) { f32x2 v = {lo, hi}; bf16x2_t b = __builtin_convertvector(v, bf16x2_t); return __builtin_bit_cast(unsigned, b); }
; __device__ __forceinline__ float fast_exp2(float x) { return __builtin_amdgcn_exp2f(x); }
; #define AT_STAGE(gbase, so, i, ldsoff) do { const int _ii = (i) < NT ? (i) : NT - 1; const size_t _go = (size_t)((tstart + _ii) & tmask) * (64 * 1024); _Pragma("unroll") for (int _i = 0; _i < 2; ++_i) \
;         __builtin_amdgcn_global_load_lds((const unsigned*)((gbase) + _go + (so)[_i]), (LAS unsigned*)(lds + (ldsoff) + (2 * w + _i) * 1024), 16, 0, 0); } while (0)
; template <bool QK, bool PV> ...
;     ...
;         {
;             const int c = dt >> 2, kt = dt & 3;
; #pragma unroll
;             for (int j = 0; j < 4; ++j) s[c][kt][j] = fast_exp2(s[c][kt][j]);
;             if (kt & 1) { const int si = kt >> 1;
;                 u32x4 wv; wv.x = cvtpk(s[c][2 * si][0], s[c][2 * si][1]); wv.y = cvtpk(s[c][2 * si][2], s[c][2 * si][3]);
;                 wv.z = cvtpk(s[c][2 * si + 1][0], s[c][2 * si + 1][1]); wv.w = cvtpk(s[c][2 * si + 1][2], s[c][2 * si + 1][3]);
;                 pn[c][si] = __builtin_bit_cast(bf16x8, wv); }
;         }
;     }
;     ...
; #pragma unroll
;     for (int c = 0; c < 2; ++c)
; #pragma unroll
;         for (int si = 0; si < 2; ++si) pf[c][si] = pn[c][si];
;     if constexpr (QK) {
; #pragma unroll
;         for (int kt = 0; kt < 4; ++kt)
; #pragma unroll
;             for (int c = 0; c < 2; ++c) {
;                 f32x4 a = tbv[kt];
; #pragma unroll
;                 for (int kk = 0; kk < 2; ++kk) { const bf16x8 kf = *(const LAS bf16x8*)(kbuf + kfo[c][kk] + kt * 4096); a = __builtin_amdgcn_mfma_f32_16x16x32_bf16(kf, qf[c][kk], a, 0, 0, 0); }
;                 s[c][kt] = a;
;             }
;     }
; __device__ __forceinline__ void attn_unit(LAS unsigned char* lds, int seq, int h, int qb, bf16_t* UQ, const bf16_t* KB, const bf16_t* VB, const float* rel_bias, const float* subln, float lam, float bmax) {
;     ...
;         AT_STAGE(kg, kso, i + 3, k_i); AT_STAGE(vg, vso, i + 2, AT_V0 + ((i + 2) & 3) * AT_TILE);
	s_add_i32 s99, s60, 3
	s_min_u32 s99, s99, s45
	s_add_i32 s99, s99, s46
	s_and_b32 s99, s99, s45
	s_lshl_b32 s99, s99, 16
	s_add_u32 s100, s47, s99
	s_addc_u32 s101, s48, 0
	s_add_i32 s99, s49, s59
	s_mov_b32 m0, s99
	s_nop 0
	global_load_lds_dwordx4 v154, s[100:101]
	s_add_i32 m0, s99, 0x400
	s_nop 0
	global_load_lds_dwordx4 v166, s[100:101]
	s_cmp_lg_u32 s54, s60
	v_mfma_f32_16x16x32_bf16 v[50:53], v[220:223], v[42:45], v[50:53]
	v_exp_f32_e32 v220, v88
	v_exp_f32_e32 v221, v89
	v_exp_f32_e32 v222, v90
	v_mfma_f32_16x16x32_bf16 v[54:57], v[224:227], v[34:37], v[54:57]
	v_exp_f32_e32 v223, v91
	v_mfma_f32_16x16x32_bf16 v[50:53], v[224:227], v[18:21], v[50:53]
	v_exp_f32_e32 v224, v94
	v_add_u32_e32 v94, s2, v182
	v_exp_f32_e32 v225, v95
	v_mfma_f32_16x16x32_bf16 v[66:69], v[216:219], v[58:61], v[66:69]
	v_exp_f32_e32 v226, v96
	v_exp_f32_e32 v95, v38
	v_exp_f32_e32 v96, v39
	v_mfma_f32_16x16x32_bf16 v[30:33], v[228:231], v[58:61], v[30:33]
	ds_read_b128 v[58:61], v94
	v_exp_f32_e32 v227, v97
	v_mfma_f32_16x16x32_bf16 v[70:73], v[216:219], v[42:45], v[70:73]
	v_exp_f32_e32 v216, v74
	v_exp_f32_e32 v217, v75
	v_exp_f32_e32 v218, v76
	v_mfma_f32_16x16x32_bf16 v[42:45], v[228:231], v[42:45], v[46:49]
	v_add_u32_e32 v230, s2, v183
	v_add_u32_e32 v231, s2, v184
	v_exp_f32_e32 v219, v77
	v_mfma_f32_16x16x32_bf16 v[66:69], v[236:239], v[34:37], v[66:69]
	v_exp_f32_e32 v228, v23
	v_exp_f32_e32 v229, v24
	v_mfma_f32_16x16x32_bf16 v[30:33], v[232:235], v[34:37], v[30:33]
	ds_read_b128 v[34:37], v230
	s_waitcnt lgkmcnt(0)
	v_mfma_f32_16x16x32_bf16 v[58:61], v[58:61], v[2:5], v[146:149]
	v_mfma_f32_16x16x32_bf16 v[70:73], v[236:239], v[18:21], v[70:73]
	v_exp_f32_e32 v236, v86
	v_exp_f32_e32 v237, v87
	v_exp_f32_e32 v238, v92
	v_mfma_f32_16x16x32_bf16 v[46:49], v[232:235], v[18:21], v[42:45]
	ds_read_b128 v[18:21], v231
	s_nop 1
	ds_read_b128 v[42:45], v94 offset:4096
	v_add_u32_e32 v232, s2, v185
	v_exp_f32_e32 v239, v93
	ds_read_b128 v[86:89], v232
	ds_read_b128 v[90:93], v230 offset:4096
	v_mfma_f32_16x16x32_bf16 v[74:77], v[34:37], v[6:9], v[58:61]
	ds_read_b128 v[34:37], v231 offset:4096
	v_exp_f32_e32 v233, v25
	v_exp_f32_e32 v234, v26
	s_waitcnt lgkmcnt(0)
	v_mfma_f32_16x16x32_bf16 v[18:21], v[18:21], v[10:13], v[146:149]
	ds_read_b128 v[58:61], v232 offset:4096
	v_exp_f32_e32 v235, v27
	v_mfma_f32_16x16x32_bf16 v[22:25], v[86:89], v[14:17], v[18:21]
	v_mfma_f32_16x16x32_bf16 v[18:21], v[42:45], v[2:5], v[138:141]
	v_exp_f32_e32 v42, v40
	v_exp_f32_e32 v43, v41
	ds_read_b128 v[38:41], v94 offset:8192
	v_mfma_f32_16x16x32_bf16 v[26:29], v[34:37], v[10:13], v[138:141]
	ds_read_b128 v[34:37], v230 offset:8192
	v_exp_f32_e32 v44, v62
	v_exp_f32_e32 v45, v65
	v_mfma_f32_16x16x32_bf16 v[86:89], v[90:93], v[6:9], v[18:21]
	s_nop 2
	v_exp_f32_e32 v20, v63
	v_exp_f32_e32 v21, v64
	v_cvt_pk_bf16_f32 v18, v95, v96
	s_waitcnt lgkmcnt(0)
	v_mfma_f32_16x16x32_bf16 v[26:29], v[58:61], v[14:17], v[26:29]
	ds_read_b128 v[58:61], v231 offset:8192
	ds_read_b128 v[62:65], v94 offset:12288
	ds_read_b128 v[94:97], v232 offset:8192
	ds_read_b128 v[138:141], v230 offset:12288
	ds_read_b128 v[146:149], v231 offset:12288
	v_mfma_f32_16x16x32_bf16 v[38:41], v[38:41], v[2:5], v[150:153]
	v_cvt_pk_bf16_f32 v19, v42, v43
	v_cvt_pk_bf16_f32 v20, v44, v20
	v_cvt_pk_bf16_f32 v21, v21, v45
	v_mfma_f32_16x16x32_bf16 v[90:93], v[34:37], v[6:9], v[38:41]
	v_cvt_pk_bf16_f32 v42, v240, v228
	v_cvt_pk_bf16_f32 v43, v229, v233
	v_cvt_pk_bf16_f32 v44, v234, v235
	s_waitcnt lgkmcnt(0)
	v_mfma_f32_16x16x32_bf16 v[34:37], v[58:61], v[10:13], v[150:153]
	v_cvt_pk_bf16_f32 v45, v241, v242
	v_cvt_pk_bf16_f32 v58, v216, v217
	v_cvt_pk_bf16_f32 v59, v218, v219
	ds_read_b128 v[150:153], v232 offset:12288
	v_mfma_f32_16x16x32_bf16 v[60:63], v[62:65], v[2:5], v[142:145]
	s_waitcnt vmcnt(4) lgkmcnt(0)
	s_barrier
	v_mfma_f32_16x16x32_bf16 v[38:41], v[94:97], v[14:17], v[34:37]
	v_mfma_f32_16x16x32_bf16 v[94:97], v[138:141], v[6:9], v[60:63]
	s_nop 1
	v_cvt_pk_bf16_f32 v34, v222, v223
	v_cvt_pk_bf16_f32 v35, v238, v239
	v_cvt_pk_bf16_f32 v36, v224, v225
	v_mfma_f32_16x16x32_bf16 v[62:65], v[146:149], v[10:13], v[142:145]
	v_cvt_pk_bf16_f32 v37, v226, v227
	v_cvt_pk_bf16_f32 v60, v236, v237
	v_cvt_pk_bf16_f32 v61, v220, v221
	s_waitcnt lgkmcnt(0)
	v_mfma_f32_16x16x32_bf16 v[62:65], v[150:153], v[14:17], v[62:65]
	s_cbranch_scc0 .LBB0_502
	s_mov_b32 s2, s59
	s_mov_b32 s59, s61
	s_branch .LBB0_514

; #define LAS __attribute__((address_space(3)))
; __device__ __forceinline__ unsigned cvtpk(float lo, float hi) { f32x2 v = {lo, hi}; bf16x2_t b = __builtin_convertvector(v, bf16x2_t); return __builtin_bit_cast(unsigned, b); }
; __device__ __forceinline__ float fast_exp2(float x) { return __builtin_amdgcn_exp2f(x); }
; #define AT_STAGE(gbase, so, i, ldsoff) do { const int _ii = (i) < NT ? (i) : NT - 1; const size_t _go = (size_t)((tstart + _ii) & tmask) * (64 * 1024); _Pragma("unroll") for (int _i = 0; _i < 2; ++_i) \
;         __builtin_amdgcn_global_load_lds((const unsigned*)((gbase) + _go + (so)[_i]), (LAS unsigned*)(lds + (ldsoff) + (2 * w + _i) * 1024), 16, 0, 0); } while (0)
; template <bool QK, bool PV> ...
;     ...
;         {
;             const int c = dt >> 2, kt = dt & 3;
; #pragma unroll
;             for (int j = 0; j < 4; ++j) s[c][kt][j] = fast_exp2(s[c][kt][j]);
;             if (kt & 1) { const int si = kt >> 1;
;                 u32x4 wv; wv.x = cvtpk(s[c][2 * si][0], s[c][2 * si][1]); wv.y = cvtpk(s[c][2 * si][2], s[c][2 * si][3]);
;                 wv.z = cvtpk(s[c][2 * si + 1][0], s[c][2 * si + 1][1]); wv.w = cvtpk(s[c][2 * si + 1][2], s[c][2 * si + 1][3]);
;                 pn[c][si] = __builtin_bit_cast(bf16x8, wv); }
;         }
;     }
;     ...
; #pragma unroll
;     for (int c = 0; c < 2; ++c)
; #pragma unroll
;         for (int si = 0; si < 2; ++si) pf[c][si] = pn[c][si];
;     if constexpr (QK) {
; #pragma unroll
;         for (int kt = 0; kt < 4; ++kt)
; #pragma unroll
;             for (int c = 0; c < 2; ++c) {
;                 f32x4 a = tbv[kt];
; #pragma unroll
;                 for (int kk = 0; kk < 2; ++kk) { const bf16x8 kf = *(const LAS bf16x8*)(kbuf + kfo[c][kk] + kt * 4096); a = __builtin_amdgcn_mfma_f32_16x16x32_bf16(kf, qf[c][kk], a, 0, 0, 0); }
;                 s[c][kt] = a;
;             }
;     }
; __device__ __forceinline__ void attn_unit(LAS unsigned char* lds, int seq, int h, int qb, bf16_t* UQ, const bf16_t* KB, const bf16_t* VB, const float* rel_bias, const float* subln, float lam, float bmax) {
;     ...
;     AT_BAR(0);
;     AT_STAGE(kg, kso, 3, AT_K0); AT_STAGE(vg, vso, 2, AT_V0 + 2 * AT_TILE);
;     AT_TB((tstart + 1) & tmask);
;     attn_step<true, false>(lds + AT_K0 + AT_TILE, 0u, kfo, vo, qf, s, pf, o, ol, tbv);
;     AT_BAR(4);
;     int k_i = AT_K0 + AT_TILE, k_n = AT_K0 + 2 * AT_TILE, k_p = AT_K0;
.LBB0_533:
	v_exp_f32_e32 v82, v42
	v_exp_f32_e32 v83, v43
	v_exp_f32_e32 v84, v44
	v_exp_f32_e32 v85, v45
	ds_read_b128 v[42:45], v67 offset:16384
	v_exp_f32_e32 v94, v22
	v_exp_f32_e32 v95, v23
	v_exp_f32_e32 v96, v24
	v_exp_f32_e32 v97, v25
	ds_read_b128 v[22:25], v69 offset:16384
	v_exp_f32_e32 v98, v46
	v_exp_f32_e32 v99, v47
	v_exp_f32_e32 v100, v48
	v_exp_f32_e32 v101, v49
	ds_read_b128 v[46:49], v66 offset:16384
	ds_read_b128 v[70:73], v67 offset:20480
	s_waitcnt lgkmcnt(0)
	v_mfma_f32_16x16x32_bf16 v[42:45], v[42:45], v[2:5], v[58:61]
	v_exp_f32_e32 v102, v38
	v_exp_f32_e32 v103, v39
	v_exp_f32_e32 v104, v40
	v_exp_f32_e32 v105, v41
	ds_read_b128 v[38:41], v68 offset:16384
	ds_read_b128 v[78:81], v69 offset:20480
	v_mfma_f32_16x16x32_bf16 v[74:77], v[22:25], v[6:9], v[42:45]
	v_exp_f32_e32 v106, v18
	v_exp_f32_e32 v107, v19
	v_exp_f32_e32 v108, v28
	ds_read_b128 v[42:45], v66 offset:20480
	v_mfma_f32_16x16x32_bf16 v[22:25], v[46:49], v[10:13], v[58:61]
	v_exp_f32_e32 v109, v29
	s_and_b32 s2, s42, 15
	s_lshl_b32 s50, s2, 1
	v_exp_f32_e32 v58, v20
	v_exp_f32_e32 v59, v21
	ds_read_b128 v[18:21], v68 offset:20480
	s_waitcnt lgkmcnt(0)
	v_mfma_f32_16x16x32_bf16 v[22:25], v[38:41], v[14:17], v[22:25]
	v_exp_f32_e32 v60, v26
	v_exp_f32_e32 v61, v27
	s_add_i32 s50, s50, 2
	v_mfma_f32_16x16x32_bf16 v[38:41], v[70:73], v[2:5], v[50:53]
	v_exp_f32_e32 v70, v30
	v_exp_f32_e32 v71, v31
	v_exp_f32_e32 v72, v32
	v_exp_f32_e32 v73, v33
	ds_read_b128 v[30:33], v67 offset:24576
	v_mfma_f32_16x16x32_bf16 v[86:89], v[78:81], v[6:9], v[38:41]
	v_exp_f32_e32 v78, v34
	v_exp_f32_e32 v79, v35
	v_exp_f32_e32 v80, v36
	ds_read_b128 v[38:41], v69 offset:24576
	v_mfma_f32_16x16x32_bf16 v[26:29], v[42:45], v[10:13], v[50:53]
	ds_read_b128 v[42:45], v66 offset:24576
	ds_read_b128 v[46:49], v67 offset:28672
	v_exp_f32_e32 v67, v37
	s_addk_i32 s51, 0xff42
	v_mfma_f32_16x16x32_bf16 v[26:29], v[18:21], v[14:17], v[26:29]
	s_add_i32 s52, s44, 3
	s_movk_i32 s55, 0x4000
	s_mov_b32 s54, 0x8000
	s_waitcnt lgkmcnt(0)
	v_mfma_f32_16x16x32_bf16 v[18:21], v[30:33], v[2:5], v[62:65]
	ds_read_b128 v[30:33], v68 offset:24576
	ds_read_b128 v[50:53], v69 offset:28672
	s_mov_b32 s53, 0x10000
	s_mov_b32 s56, 0
	v_mfma_f32_16x16x32_bf16 v[90:93], v[38:41], v[6:9], v[18:21]
	s_mov_b32 s2, 0
	s_nop 1
	v_cvt_pk_bf16_f32 v18, v70, v71
	v_cvt_pk_bf16_f32 v19, v72, v73
	ds_read_b128 v[70:73], v66 offset:28672
	v_mfma_f32_16x16x32_bf16 v[34:37], v[42:45], v[10:13], v[62:65]
	v_cvt_pk_bf16_f32 v20, v78, v79
	v_cvt_pk_bf16_f32 v21, v80, v67
	v_cvt_pk_bf16_f32 v42, v106, v107
	ds_read_b128 v[62:65], v68 offset:28672
	s_waitcnt lgkmcnt(0)
	v_mfma_f32_16x16x32_bf16 v[38:41], v[30:33], v[14:17], v[34:37]
	s_waitcnt vmcnt(4) lgkmcnt(0)
	s_barrier
	v_cvt_pk_bf16_f32 v43, v58, v59
	v_cvt_pk_bf16_f32 v44, v60, v61
	v_mfma_f32_16x16x32_bf16 v[30:33], v[46:49], v[2:5], v[54:57]
	v_cvt_pk_bf16_f32 v34, v94, v95
	v_cvt_pk_bf16_f32 v35, v96, v97
	v_cvt_pk_bf16_f32 v45, v108, v109
	v_mfma_f32_16x16x32_bf16 v[94:97], v[50:53], v[6:9], v[30:33]
	v_cvt_pk_bf16_f32 v36, v102, v103
	v_cvt_pk_bf16_f32 v37, v104, v105
	v_cvt_pk_bf16_f32 v58, v82, v83
	v_mfma_f32_16x16x32_bf16 v[30:33], v[70:73], v[10:13], v[54:57]
	v_cvt_pk_bf16_f32 v59, v84, v85
	v_cvt_pk_bf16_f32 v60, v98, v99
	v_cvt_pk_bf16_f32 v61, v100, v101
	v_mfma_f32_16x16x32_bf16 v[62:65], v[62:65], v[14:17], v[30:33]
	s_nop 3
	v_mov_b32_e32 v30, 0
	v_mov_b32_e32 v31, v30
	v_mov_b32_e32 v32, v30
	v_mov_b32_e32 v33, v30
	v_mov_b32_e32 v46, v30
	v_mov_b32_e32 v47, v30
	v_mov_b32_e32 v48, v30
	v_mov_b32_e32 v49, v30
	v_mov_b32_e32 v54, v30
	v_mov_b32_e32 v55, v30
	v_mov_b32_e32 v56, v30
	v_mov_b32_e32 v57, v30
	v_mov_b32_e32 v50, v30
	v_mov_b32_e32 v51, v30
	v_mov_b32_e32 v52, v30
	v_mov_b32_e32 v53, v30
	v_mov_b32_e32 v66, v30
	v_mov_b32_e32 v67, v30
	v_mov_b32_e32 v68, v30
	v_mov_b32_e32 v69, v30
	v_mov_b32_e32 v70, v30
	v_mov_b32_e32 v71, v30
	v_mov_b32_e32 v72, v30
	v_mov_b32_e32 v73, v30
	v_mov_b32_e32 v78, v30
	v_mov_b32_e32 v79, v30
	v_mov_b32_e32 v80, v30
	v_mov_b32_e32 v81, v30
	v_mov_b32_e32 v82, v30
	v_mov_b32_e32 v83, v30
	v_mov_b32_e32 v84, v30
	v_mov_b32_e32 v85, v30
	v_mov_b32_e32 v98, v30
	v_mov_b32_e32 v99, v30
	v_mov_b32_e32 v100, v30
	v_mov_b32_e32 v101, v30
	v_mov_b32_e32 v102, v30
	v_mov_b32_e32 v103, v30
	v_mov_b32_e32 v104, v30
	v_mov_b32_e32 v105, v30
	v_mov_b32_e32 v106, v30
	v_mov_b32_e32 v107, v30
	v_mov_b32_e32 v108, v30
	v_mov_b32_e32 v109, v30
	v_mov_b32_e32 v110, v30
	v_mov_b32_e32 v111, v30
	v_mov_b32_e32 v112, v30
	v_mov_b32_e32 v113, v30
	v_mov_b32_e32 v114, v30
	v_mov_b32_e32 v115, v30
	v_mov_b32_e32 v116, v30
	v_mov_b32_e32 v117, v30
	v_mov_b32_e32 v118, v30
	v_mov_b32_e32 v119, v30
	v_mov_b32_e32 v120, v30
	v_mov_b32_e32 v121, v30
	v_mov_b32_e32 v122, v30
	v_mov_b32_e32 v123, v30
	v_mov_b32_e32 v124, v30
	v_mov_b32_e32 v125, v30
	v_mov_b32_e32 v134, v30
	v_mov_b32_e32 v135, v30
	v_mov_b32_e32 v136, v30
	v_mov_b32_e32 v137, v30
	v_mov_b32_e32 v130, v30
	v_mov_b32_e32 v131, v30
	v_mov_b32_e32 v132, v30
	v_mov_b32_e32 v133, v30
	v_mov_b32_e32 v126, v30
	v_mov_b32_e32 v127, v30
	v_mov_b32_e32 v128, v30
	v_mov_b32_e32 v129, v30
	v_readfirstlane_b32 s98, v171
	s_nop 3
	s_lshr_b32 s98, s98, 6
	s_cmp_lt_u32 s98, 4
	s_cbranch_scc1 .Lat_xskip_p
	s_barrier
; #define AT_STAGE(gbase, so, i, ldsoff) do { const int _ii = (i) < NT ? (i) : NT - 1; const size_t _go = (size_t)((tstart + _ii) & tmask) * (64 * 1024); _Pragma("unroll") for (int _i = 0; _i < 2; ++_i) \
;         __builtin_amdgcn_global_load_lds((const unsigned*)((gbase) + _go + (so)[_i]), (LAS unsigned*)(lds + (ldsoff) + (2 * w + _i) * 1024), 16, 0, 0); } while (0)
; __device__ __forceinline__ void attn_unit(LAS unsigned char* lds, int seq, int h, int qb, bf16_t* UQ, const bf16_t* KB, const bf16_t* VB, const float* rel_bias, const float* subln, float lam, float bmax) {
;     ...
;     for (int i = 1; i < NT - 1; ++i) {
;         AT_STAGE(kg, kso, i + 3, k_i); AT_STAGE(vg, vso, i + 2, AT_V0 + ((i + 2) & 3) * AT_TILE);
;         AT_TB((tstart + i + 1) & tmask);
.Lat_xskip_p:
.LBB0_534:
	s_mov_b32 s3, s56
	s_add_i32 s56, s56, 1
	s_add_i32 s22, s3, 3
	s_min_u32 s22, s22, 31
	s_add_i32 s22, s22, s44
	s_lshl_b32 s22, s22, 16
	s_and_b32 s22, s22, 0x1f0000
	s_add_u32 s22, s20, s22
	s_addc_u32 s23, s48, 0
	s_add_i32 s57, s53, 0xffffc000
	s_and_b32 s57, s57, 0xc000
	s_add_i32 s57, s47, s57
	s_add_i32 m0, s57, 0xc000
	s_nop 0
	global_load_lds_dwordx4 v164, s[22:23]
	s_add_i32 m0, s57, 0xc400
	s_mov_b32 s57, s54
	global_load_lds_dwordx4 v168, s[22:23]
	s_mov_b32 s54, s2
	s_add_i32 s2, s50, s3
	s_and_b32 s58, s2, 31
	s_lshl_b32 s2, s58, 6
	s_sub_i32 s3, s2, s49
	s_cmp_lt_i32 s2, s51
	s_cselect_b64 s[22:23], -1, 0
	s_cmpk_gt_i32 s3, 0x7f
	s_cselect_b64 s[2:3], -1, 0
	s_or_b64 s[60:61], s[22:23], s[2:3]
	s_mov_b64 s[22:23], -1
	s_and_b64 vcc, exec, s[60:61]
	s_cbranch_vccnz .LBB0_536
	v_lshl_add_u32 v142, s58, 8, v214
	v_add_u32_e32 v139, 4, v142
	v_add_u32_e32 v140, 8, v142
	v_add_u32_e32 v141, 12, v142
	v_add_u32_e32 v146, 0x4c, v142
	v_med3_i32 v138, v142, 0, v213
	v_med3_i32 v139, v139, 0, v213
	v_med3_i32 v140, v140, 0, v213
	v_med3_i32 v141, v141, 0, v213
	v_add_u32_e32 v143, 64, v142
	v_add_u32_e32 v144, 0x44, v142
	v_add_u32_e32 v145, 0x48, v142
	v_med3_i32 v146, v146, 0, v213
	v_add_u32_e32 v138, s27, v138
	v_add_u32_e32 v139, s27, v139
	v_add_u32_e32 v140, s27, v140
	v_add_u32_e32 v141, s27, v141
	v_med3_i32 v143, v143, 0, v213
	v_med3_i32 v144, v144, 0, v213
	v_med3_i32 v145, v145, 0, v213
	v_add_u32_e32 v150, s27, v146
	v_add_u32_e32 v143, s27, v143
	v_add_u32_e32 v144, s27, v144
	v_add_u32_e32 v145, s27, v145
	ds_read_b32 v146, v138
	ds_read_b32 v147, v139
	ds_read_b32 v148, v140
	ds_read_b32 v149, v141
	ds_read_b32 v138, v143
	ds_read_b32 v139, v144
	ds_read_b32 v140, v145
	ds_read_b32 v141, v150
	v_add_u32_e32 v150, 0x8c, v142
	v_med3_i32 v150, v150, 0, v213
	v_add_u32_e32 v153, s27, v150
	v_add_u32_e32 v150, 0xc0, v142
	v_med3_i32 v150, v150, 0, v213
	v_add_u32_e32 v217, s27, v150
	v_add_u32_e32 v150, 0xc4, v142
	v_add_u32_e32 v143, 0x80, v142
	v_add_u32_e32 v144, 0x84, v142
	v_add_u32_e32 v145, 0x88, v142
	v_med3_i32 v150, v150, 0, v213
	v_med3_i32 v143, v143, 0, v213
	v_med3_i32 v144, v144, 0, v213
	v_med3_i32 v145, v145, 0, v213
	v_add_u32_e32 v218, s27, v150
	v_add_u32_e32 v150, 0xc8, v142
	v_add_u32_e32 v142, 0xcc, v142
	v_add_u32_e32 v143, s27, v143
	v_add_u32_e32 v144, s27, v144
	v_add_u32_e32 v145, s27, v145
	v_med3_i32 v150, v150, 0, v213
	v_med3_i32 v142, v142, 0, v213
	v_add_u32_e32 v219, s27, v150
	v_add_u32_e32 v220, s27, v142
	ds_read_b32 v150, v143
	ds_read_b32 v151, v144
	ds_read_b32 v152, v145
	ds_read_b32 v153, v153
	ds_read_b32 v142, v217
	ds_read_b32 v143, v218
	ds_read_b32 v144, v219
	ds_read_b32 v145, v220
	s_mov_b64 s[22:23], 0

; #define AT_TR4(slot, d) do { const unsigned _a = vaddr + (unsigned)vo[d]; AT_TR(r[slot][0], _a, 0); AT_TR(r[slot][1], _a, 16 * 256); AT_TR(r[slot][2], _a, 32 * 256); AT_TR(r[slot][3], _a, 48 * 256); } while (0)
; #define AT_TR4(slot, d) do { const unsigned _a = vaddr + (unsigned)vo[d]; AT_TR(r[slot][0], _a, 0); AT_TR(r[slot][1], _a, 16 * 256); AT_TR(r[slot][2], _a, 32 * 256); AT_TR(r[slot][3], _a, 48 * 256); } while (0)
; template <bool QK, bool PV> ...
;     ...
;     if constexpr (PV) { AT_TR4(0, 0); AT_TR4(1, 1);
;         const bf16x8 ones = (bf16x8){0x3f80, 0x3f80, 0x3f80, 0x3f80, 0x3f80, 0x3f80, 0x3f80, 0x3f80};
; #pragma unroll
;         for (int c = 0; c < 2; ++c)
; #pragma unroll
;             for (int si = 0; si < 2; ++si) ol[c] = __builtin_amdgcn_mfma_f32_16x16x32_bf16(ones, pf[c][si], ol[c], 0, 0, 0); }
; #pragma unroll
;     for (int dt = 0; dt < 8; ++dt) {
;         if constexpr (PV) {
;             const int cb = dt % 3;
;             if (dt < 6) { AT_TR4((dt + 2) % 3, dt + 2); asm volatile("s_waitcnt lgkmcnt(8)" : "+v"(r[cb][0]), "+v"(r[cb][1]), "+v"(r[cb][2]), "+v"(r[cb][3])); }
;             else if (dt == 6) asm volatile("s_waitcnt lgkmcnt(4)" : "+v"(r[cb][0]), "+v"(r[cb][1]), "+v"(r[cb][2]), "+v"(r[cb][3]));
;             else asm volatile("s_waitcnt lgkmcnt(0)" : "+v"(r[cb][0]), "+v"(r[cb][1]), "+v"(r[cb][2]), "+v"(r[cb][3]));
; #pragma unroll
;             for (int si = 0; si < 2; ++si) {
;                 const s16x4 lo = r[cb][2 * si], hi = r[cb][2 * si + 1];
;                 const bf16x8 vf = (bf16x8){lo[0], lo[1], lo[2], lo[3], hi[0], hi[1], hi[2], hi[3]};
;                 o[0][dt] = __builtin_amdgcn_mfma_f32_16x16x32_bf16(vf, pf[0][si], o[0][dt], 0, 0, 0);
;                 o[1][dt] = __builtin_amdgcn_mfma_f32_16x16x32_bf16(vf, pf[1][si], o[1][dt], 0, 0, 0);
;             }
;         }
.LBB0_538:
	v_mov_b64_e32 v[220:221], s[6:7]
	v_mov_b64_e32 v[218:219], s[4:5]
	s_and_b32 s2, s53, 0xc000
	s_add_i32 s2, s2, 0
	s_add_i32 s2, s2, 0xc000
	v_add_u32_e32 v217, s2, v175
	v_mfma_f32_16x16x32_bf16 v[134:137], v[218:221], v[58:61], v[134:137]
	ds_read_b64_tr_b16 v[222:223], v217 offset:0
	ds_read_b64_tr_b16 v[224:225], v217 offset:0x1000
	ds_read_b64_tr_b16 v[226:227], v217 offset:0x2000
	v_mfma_f32_16x16x32_bf16 v[130:133], v[218:221], v[42:45], v[130:133]
	ds_read_b64_tr_b16 v[228:229], v217 offset:0x3000
	v_add_u32_e32 v217, s2, v185
	ds_read_b64_tr_b16 v[230:231], v217 offset:0
	v_mfma_f32_16x16x32_bf16 v[134:137], v[218:221], v[34:37], v[134:137]
	ds_read_b64_tr_b16 v[232:233], v217 offset:0x1000
	ds_read_b64_tr_b16 v[234:235], v217 offset:0x2000
	ds_read_b64_tr_b16 v[236:237], v217 offset:0x3000
	v_mfma_f32_16x16x32_bf16 v[130:133], v[218:221], v[18:21], v[130:133]
	v_add_u32_e32 v217, s2, v186
	ds_read_b64_tr_b16 v[218:219], v217 offset:0
	ds_read_b64_tr_b16 v[220:221], v217 offset:0x1000
	ds_read_b64_tr_b16 v[238:239], v217 offset:0x2000
	ds_read_b64_tr_b16 v[240:241], v217 offset:0x3000
	s_waitcnt lgkmcnt(8)
	v_add_u32_e32 v217, s2, v187
	v_mfma_f32_16x16x32_bf16 v[126:129], v[222:225], v[58:61], v[126:129]
	v_exp_f32_e32 v242, v28
	v_exp_f32_e32 v243, v29
	s_addk_i32 s53, 0x4000
	v_mfma_f32_16x16x32_bf16 v[122:125], v[222:225], v[42:45], v[122:125]
	ds_read_b64_tr_b16 v[222:223], v217 offset:0
	ds_read_b64_tr_b16 v[224:225], v217 offset:0x1000
	v_mfma_f32_16x16x32_bf16 v[126:129], v[226:229], v[34:37], v[126:129]
	v_mfma_f32_16x16x32_bf16 v[122:125], v[226:229], v[18:21], v[122:125]
	ds_read_b64_tr_b16 v[226:227], v217 offset:0x2000
	ds_read_b64_tr_b16 v[228:229], v217 offset:0x3000
	s_waitcnt lgkmcnt(8)
	v_add_u32_e32 v217, s2, v188
	v_mfma_f32_16x16x32_bf16 v[114:117], v[230:233], v[58:61], v[114:117]
	v_mfma_f32_16x16x32_bf16 v[118:121], v[230:233], v[42:45], v[118:121]
	ds_read_b64_tr_b16 v[230:231], v217 offset:0
	ds_read_b64_tr_b16 v[232:233], v217 offset:0x1000
	v_mfma_f32_16x16x32_bf16 v[114:117], v[234:237], v[34:37], v[114:117]
	v_mfma_f32_16x16x32_bf16 v[118:121], v[234:237], v[18:21], v[118:121]
	ds_read_b64_tr_b16 v[234:235], v217 offset:0x2000
	ds_read_b64_tr_b16 v[236:237], v217 offset:0x3000
	s_waitcnt lgkmcnt(8)
	v_add_u32_e32 v217, s2, v189
	v_mfma_f32_16x16x32_bf16 v[106:109], v[218:221], v[58:61], v[106:109]
	v_mfma_f32_16x16x32_bf16 v[110:113], v[218:221], v[42:45], v[110:113]
	ds_read_b64_tr_b16 v[218:219], v217 offset:0
	ds_read_b64_tr_b16 v[220:221], v217 offset:0x1000
	v_mfma_f32_16x16x32_bf16 v[106:109], v[238:241], v[34:37], v[106:109]
	v_mfma_f32_16x16x32_bf16 v[110:113], v[238:241], v[18:21], v[110:113]
	ds_read_b64_tr_b16 v[238:239], v217 offset:0x2000
	ds_read_b64_tr_b16 v[240:241], v217 offset:0x3000
	s_waitcnt lgkmcnt(8)
	v_add_u32_e32 v217, s2, v190
	v_mfma_f32_16x16x32_bf16 v[98:101], v[222:225], v[58:61], v[98:101]
	v_mfma_f32_16x16x32_bf16 v[102:105], v[222:225], v[42:45], v[102:105]
	ds_read_b64_tr_b16 v[222:223], v217 offset:0
	ds_read_b64_tr_b16 v[224:225], v217 offset:0x1000
	v_mfma_f32_16x16x32_bf16 v[98:101], v[226:229], v[34:37], v[98:101]
	v_mfma_f32_16x16x32_bf16 v[102:105], v[226:229], v[18:21], v[102:105]
	ds_read_b64_tr_b16 v[226:227], v217 offset:0x2000
	ds_read_b64_tr_b16 v[228:229], v217 offset:0x3000
	s_waitcnt lgkmcnt(8)
	v_add_u32_e32 v217, s2, v191
	v_mfma_f32_16x16x32_bf16 v[78:81], v[230:233], v[58:61], v[78:81]
	s_add_i32 s2, s57, 0
	s_cmp_lg_u32 s56, 30
	v_mfma_f32_16x16x32_bf16 v[82:85], v[230:233], v[42:45], v[82:85]
	ds_read_b64_tr_b16 v[230:231], v217 offset:0
	ds_read_b64_tr_b16 v[232:233], v217 offset:0x1000
	v_mfma_f32_16x16x32_bf16 v[78:81], v[234:237], v[34:37], v[78:81]
	v_mfma_f32_16x16x32_bf16 v[82:85], v[234:237], v[18:21], v[82:85]
	ds_read_b64_tr_b16 v[234:235], v217 offset:0x2000
	ds_read_b64_tr_b16 v[236:237], v217 offset:0x3000
	s_waitcnt lgkmcnt(8)
	s_waitcnt lgkmcnt(4)
	v_exp_f32_e32 v217, v74
	v_mfma_f32_16x16x32_bf16 v[54:57], v[222:225], v[58:61], v[54:57]
	s_waitcnt lgkmcnt(0)
	s_barrier
; #define LAS __attribute__((address_space(3)))
; __device__ __forceinline__ unsigned cvtpk(float lo, float hi) { f32x2 v = {lo, hi}; bf16x2_t b = __builtin_convertvector(v, bf16x2_t); return __builtin_bit_cast(unsigned, b); }
; __device__ __forceinline__ float fast_exp2(float x) { return __builtin_amdgcn_exp2f(x); }
; #define AT_STAGE(gbase, so, i, ldsoff) do { const int _ii = (i) < NT ? (i) : NT - 1; const size_t _go = (size_t)((tstart + _ii) & tmask) * (64 * 1024); _Pragma("unroll") for (int _i = 0; _i < 2; ++_i) \
;         __builtin_amdgcn_global_load_lds((const unsigned*)((gbase) + _go + (so)[_i]), (LAS unsigned*)(lds + (ldsoff) + (2 * w + _i) * 1024), 16, 0, 0); } while (0)
; template <bool QK, bool PV> ...
;     ...
;         {
;             const int c = dt >> 2, kt = dt & 3;
; #pragma unroll
;             for (int j = 0; j < 4; ++j) s[c][kt][j] = fast_exp2(s[c][kt][j]);
;             if (kt & 1) { const int si = kt >> 1;
;                 u32x4 wv; wv.x = cvtpk(s[c][2 * si][0], s[c][2 * si][1]); wv.y = cvtpk(s[c][2 * si][2], s[c][2 * si][3]);
;                 wv.z = cvtpk(s[c][2 * si + 1][0], s[c][2 * si + 1][1]); wv.w = cvtpk(s[c][2 * si + 1][2], s[c][2 * si + 1][3]);
;                 pn[c][si] = __builtin_bit_cast(bf16x8, wv); }
;         }
;     }
;     ...
; #pragma unroll
;     for (int c = 0; c < 2; ++c)
; #pragma unroll
;         for (int si = 0; si < 2; ++si) pf[c][si] = pn[c][si];
;     if constexpr (QK) {
; #pragma unroll
;         for (int kt = 0; kt < 4; ++kt)
; #pragma unroll
;             for (int c = 0; c < 2; ++c) {
;                 f32x4 a = tbv[kt];
; #pragma unroll
;                 for (int kk = 0; kk < 2; ++kk) { const bf16x8 kf = *(const LAS bf16x8*)(kbuf + kfo[c][kk] + kt * 4096); a = __builtin_amdgcn_mfma_f32_16x16x32_bf16(kf, qf[c][kk], a, 0, 0, 0); }
;                 s[c][kt] = a;
;             }
;     }
; __device__ __forceinline__ void attn_unit(LAS unsigned char* lds, int seq, int h, int qb, bf16_t* UQ, const bf16_t* KB, const bf16_t* VB, const float* rel_bias, const float* subln, float lam, float bmax) {
;     ...
;         AT_STAGE(kg, kso, i + 3, k_i); AT_STAGE(vg, vso, i + 2, AT_V0 + ((i + 2) & 3) * AT_TILE);
	s_min_u32 s99, s56, 28
	s_add_i32 s99, s52, s99
	s_lshl_b32 s99, s99, 16
	s_and_b32 s99, s99, 0x1f0000
	s_add_u32 s100, s45, s99
	s_addc_u32 s101, s46, 0
	s_add_i32 s99, s47, s55
	s_mov_b32 m0, s99
	s_nop 0
	global_load_lds_dwordx4 v154, s[100:101]
	s_add_i32 m0, s99, 0x400
	s_nop 0
	global_load_lds_dwordx4 v166, s[100:101]
	s_cmp_lg_u32 s56, 30
	v_mfma_f32_16x16x32_bf16 v[50:53], v[222:225], v[42:45], v[50:53]
	v_exp_f32_e32 v222, v88
	v_exp_f32_e32 v223, v89
	v_exp_f32_e32 v224, v90
	v_mfma_f32_16x16x32_bf16 v[54:57], v[226:229], v[34:37], v[54:57]
	v_exp_f32_e32 v225, v91
	v_mfma_f32_16x16x32_bf16 v[50:53], v[226:229], v[18:21], v[50:53]
	v_exp_f32_e32 v226, v94
	v_add_u32_e32 v94, s2, v176
	v_exp_f32_e32 v227, v95
	v_mfma_f32_16x16x32_bf16 v[66:69], v[218:221], v[58:61], v[66:69]
	v_exp_f32_e32 v228, v96
	v_exp_f32_e32 v95, v38
	v_exp_f32_e32 v96, v39
	v_mfma_f32_16x16x32_bf16 v[30:33], v[230:233], v[58:61], v[30:33]
	ds_read_b128 v[58:61], v94
	v_exp_f32_e32 v229, v97
	v_mfma_f32_16x16x32_bf16 v[70:73], v[218:221], v[42:45], v[70:73]
	v_exp_f32_e32 v218, v75
	v_exp_f32_e32 v219, v76
	v_exp_f32_e32 v220, v77
	v_mfma_f32_16x16x32_bf16 v[42:45], v[230:233], v[42:45], v[46:49]
	v_add_u32_e32 v232, s2, v182
	v_add_u32_e32 v233, s2, v183
	v_exp_f32_e32 v221, v86
	v_mfma_f32_16x16x32_bf16 v[66:69], v[238:241], v[34:37], v[66:69]
	v_exp_f32_e32 v230, v23
	v_exp_f32_e32 v231, v24
	v_mfma_f32_16x16x32_bf16 v[30:33], v[234:237], v[34:37], v[30:33]
	ds_read_b128 v[34:37], v232
	s_waitcnt lgkmcnt(0)
	v_mfma_f32_16x16x32_bf16 v[58:61], v[58:61], v[2:5], v[146:149]
	v_mfma_f32_16x16x32_bf16 v[70:73], v[238:241], v[18:21], v[70:73]
	v_exp_f32_e32 v238, v87
	v_exp_f32_e32 v239, v92
	v_exp_f32_e32 v240, v93
	v_mfma_f32_16x16x32_bf16 v[46:49], v[234:237], v[18:21], v[42:45]
	ds_read_b128 v[18:21], v233
	s_nop 1
	ds_read_b128 v[42:45], v94 offset:4096
	v_add_u32_e32 v234, s2, v184
	ds_read_b128 v[86:89], v234
	ds_read_b128 v[90:93], v232 offset:4096
	v_mfma_f32_16x16x32_bf16 v[74:77], v[34:37], v[6:9], v[58:61]
	ds_read_b128 v[34:37], v233 offset:4096
	v_exp_f32_e32 v241, v22
	v_exp_f32_e32 v235, v25
	s_waitcnt lgkmcnt(0)
	v_mfma_f32_16x16x32_bf16 v[18:21], v[18:21], v[10:13], v[146:149]
	ds_read_b128 v[58:61], v234 offset:4096
	v_exp_f32_e32 v236, v26
	v_exp_f32_e32 v237, v27
	v_mfma_f32_16x16x32_bf16 v[22:25], v[86:89], v[14:17], v[18:21]
	v_mfma_f32_16x16x32_bf16 v[18:21], v[42:45], v[2:5], v[138:141]
	v_exp_f32_e32 v42, v40
	v_exp_f32_e32 v43, v41
	ds_read_b128 v[38:41], v94 offset:8192
	v_mfma_f32_16x16x32_bf16 v[26:29], v[34:37], v[10:13], v[138:141]
	ds_read_b128 v[34:37], v232 offset:8192
	v_exp_f32_e32 v44, v62
	v_exp_f32_e32 v45, v65
	v_mfma_f32_16x16x32_bf16 v[86:89], v[90:93], v[6:9], v[18:21]
	s_nop 2
	v_exp_f32_e32 v20, v63
	v_exp_f32_e32 v21, v64
	v_cvt_pk_bf16_f32 v18, v95, v96
	s_waitcnt lgkmcnt(0)
	v_mfma_f32_16x16x32_bf16 v[26:29], v[58:61], v[14:17], v[26:29]
	ds_read_b128 v[58:61], v233 offset:8192
	ds_read_b128 v[62:65], v94 offset:12288
	ds_read_b128 v[94:97], v234 offset:8192
	ds_read_b128 v[138:141], v232 offset:12288
	ds_read_b128 v[146:149], v233 offset:12288
	v_mfma_f32_16x16x32_bf16 v[38:41], v[38:41], v[2:5], v[150:153]
	v_cvt_pk_bf16_f32 v19, v42, v43
	v_cvt_pk_bf16_f32 v20, v44, v20
	v_cvt_pk_bf16_f32 v21, v21, v45
	v_mfma_f32_16x16x32_bf16 v[90:93], v[34:37], v[6:9], v[38:41]
	v_cvt_pk_bf16_f32 v42, v241, v230
	v_cvt_pk_bf16_f32 v43, v231, v235
	v_cvt_pk_bf16_f32 v44, v236, v237
	s_waitcnt lgkmcnt(0)
	v_mfma_f32_16x16x32_bf16 v[34:37], v[58:61], v[10:13], v[150:153]
	v_cvt_pk_bf16_f32 v45, v242, v243
	v_cvt_pk_bf16_f32 v58, v217, v218
	v_cvt_pk_bf16_f32 v59, v219, v220
	ds_read_b128 v[150:153], v234 offset:12288
	v_mfma_f32_16x16x32_bf16 v[60:63], v[62:65], v[2:5], v[142:145]
	s_waitcnt vmcnt(4) lgkmcnt(0)
	s_barrier
	v_mfma_f32_16x16x32_bf16 v[38:41], v[94:97], v[14:17], v[34:37]
	v_mfma_f32_16x16x32_bf16 v[94:97], v[138:141], v[6:9], v[60:63]
	s_nop 1
	v_cvt_pk_bf16_f32 v34, v224, v225
	v_cvt_pk_bf16_f32 v35, v239, v240
	v_cvt_pk_bf16_f32 v36, v226, v227
	v_mfma_f32_16x16x32_bf16 v[62:65], v[146:149], v[10:13], v[142:145]
	v_cvt_pk_bf16_f32 v37, v228, v229
	v_cvt_pk_bf16_f32 v60, v221, v238
	v_cvt_pk_bf16_f32 v61, v222, v223
	s_waitcnt lgkmcnt(0)
	v_mfma_f32_16x16x32_bf16 v[62:65], v[150:153], v[14:17], v[62:65]
	s_cbranch_scc0 .LBB0_522
	s_mov_b32 s2, s55
	s_mov_b32 s55, s57
	s_branch .LBB0_534

; __global__ void __launch_bounds__(512, 2) fwd_megakernel(Params P) {
	.amdhsa_kernel _Z14fwd_megakernel6Params
		.amdhsa_group_segment_fixed_size 0
		.amdhsa_private_segment_fixed_size 0
		.amdhsa_kernarg_size 488
		.amdhsa_user_sgpr_count 2
		.amdhsa_user_sgpr_dispatch_ptr 0
		.amdhsa_user_sgpr_queue_ptr 0
		.amdhsa_user_sgpr_kernarg_segment_ptr 1
		.amdhsa_user_sgpr_dispatch_id 0
		.amdhsa_user_sgpr_kernarg_preload_length 0
		.amdhsa_user_sgpr_kernarg_preload_offset 0
		.amdhsa_user_sgpr_private_segment_size 0
		.amdhsa_uses_dynamic_stack 0
		.amdhsa_enable_private_segment 0
		.amdhsa_system_sgpr_workgroup_id_x 1
		.amdhsa_system_sgpr_workgroup_id_y 0
		.amdhsa_system_sgpr_workgroup_id_z 0
		.amdhsa_system_sgpr_workgroup_info 0
		.amdhsa_system_vgpr_workitem_id 2
		.amdhsa_next_free_vgpr 247
		.amdhsa_next_free_sgpr 102
		.amdhsa_accum_offset 248
		.amdhsa_reserve_vcc 1
		.amdhsa_float_round_mode_32 0
		.amdhsa_float_round_mode_16_64 0
		.amdhsa_float_denorm_mode_32 3
		.amdhsa_float_denorm_mode_16_64 3
		.amdhsa_dx10_clamp 1
		.amdhsa_ieee_mode 1
		.amdhsa_fp16_overflow 0
		.amdhsa_tg_split 0
		.amdhsa_exception_fp_ieee_invalid_op 0
		.amdhsa_exception_fp_denorm_src 0
		.amdhsa_exception_fp_ieee_div_zero 0
		.amdhsa_exception_fp_ieee_overflow 0
		.amdhsa_exception_fp_ieee_underflow 0
		.amdhsa_exception_fp_ieee_inexact 0
		.amdhsa_exception_int_div_zero 0
	.end_amdhsa_kernel

; __global__ void __launch_bounds__(512, 2) fwd_megakernel(Params P) {
amdhsa.kernels:
  - .agpr_count:     0
    .args:
      - .offset:         0
        .size:           232
        .value_kind:     by_value
      - .offset:         232
        .size:           4
        .value_kind:     hidden_block_count_x
      - .offset:         236
        .size:           4
        .value_kind:     hidden_block_count_y
      - .offset:         240
        .size:           4
        .value_kind:     hidden_block_count_z
      - .offset:         244
        .size:           2
        .value_kind:     hidden_group_size_x
      - .offset:         246
        .size:           2
        .value_kind:     hidden_group_size_y
      - .offset:         248
        .size:           2
        .value_kind:     hidden_group_size_z
      - .offset:         250
        .size:           2
        .value_kind:     hidden_remainder_x
      - .offset:         252
        .size:           2
        .value_kind:     hidden_remainder_y
      - .offset:         254
        .size:           2
        .value_kind:     hidden_remainder_z
      - .offset:         272
        .size:           8
        .value_kind:     hidden_global_offset_x
      - .offset:         280
        .size:           8
        .value_kind:     hidden_global_offset_y
      - .offset:         288
        .size:           8
        .value_kind:     hidden_global_offset_z
      - .offset:         296
        .size:           2
        .value_kind:     hidden_grid_dims
      - .offset:         320
        .size:           8
        .value_kind:     hidden_multigrid_sync_arg
      - .offset:         352
        .size:           4
        .value_kind:     hidden_dynamic_lds_size
    .group_segment_fixed_size: 0
    .kernarg_segment_align: 8
    .kernarg_segment_size: 488
    .language:       OpenCL C
    .language_version:
      - 2
      - 0
    .max_flat_workgroup_size: 512
    .name:           _Z14fwd_megakernel6Params
    .private_segment_fixed_size: 0
    .sgpr_count:     108
    .sgpr_spill_count: 25
    .symbol:         _Z14fwd_megakernel6Params.kd
    .uniform_work_group_size: 1
    .uses_dynamic_stack: false
    .vgpr_count:     247
    .vgpr_spill_count: 0
    .wavefront_size: 64
